# GroupNorm row groups assigned XCD-contiguously (token-shift predecessor rows hit the same L2)
# baseline (speedup 1.0000x reference)
.LBB0_1301:
	s_cmp_lt_i32 s30, 9
	s_cselect_b64 s[8:9], -1, 0
	s_and_b64 s[10:11], s[8:9], s[6:7]
	s_andn2_b64 vcc, exec, s[10:11]
	s_cbranch_vccnz .LBB0_1581
	s_load_dwordx16 s[12:27], s[0:1], 0xa0
	s_load_dwordx2 s[70:71], s[0:1], 0xf0
	s_load_dwordx4 s[36:39], s[0:1], 0xe0
	s_load_dwordx4 s[40:43], s[0:1], 0x168
	s_load_dwordx2 s[58:59], s[0:1], 0x70
	s_lshl_b32 s74, s2, 3
	s_load_dwordx4 s[44:47], s[0:1], 0x18
	s_load_dwordx2 s[72:73], s[0:1], 0x28
	v_add_u32_e32 v18, s74, v230
	s_and_b32 s75, s2, 7
	s_lshl_b32 s75, s75, 5
	s_lshr_b32 s76, s2, 3
	s_add_i32 s75, s75, s76
	s_lshl_b32 s75, s75, 3
	v_add_u32_e32 v17, s75, v230
	s_waitcnt lgkmcnt(0)
	s_add_u32 s60, s42, 0x2bf00000
	s_addc_u32 s61, s43, 0
	s_add_u32 s62, s42, 0x1f380000
	s_addc_u32 s63, s43, 0
	v_ashrrev_i32_e32 v19, 4, v17
	s_movk_i32 s3, 0x800
	s_add_u32 s64, s42, 0x16800000
	v_cmp_gt_i32_e32 vcc, s3, v19
	s_addc_u32 s65, s43, 0
	s_and_saveexec_b64 s[66:67], vcc
	s_cbranch_execz .LBB0_1305
	v_lshlrev_b32_e32 v0, 6, v17
	s_movk_i32 s3, 0x3c0
	v_and_or_b32 v2, v0, s3, v136
	v_lshlrev_b32_e32 v4, 2, v2
	global_load_dword v20, v4, s[14:15]
	global_load_dword v21, v4, s[16:17]
	global_load_dword v22, v4, s[18:19]
	global_load_dword v23, v4, s[20:21]
	global_load_dword v24, v4, s[38:39]
	global_load_dword v25, v4, s[58:59]
	v_mov_b32_e32 v5, 0
	v_lshl_add_u64 v[0:1], s[58:59], 0, v[4:5]
	s_movk_i32 s3, 0x2000
	v_or_b32_e32 v3, 0x1000, v4
	v_add_co_u32_e32 v0, vcc, s3, v0
	s_ashr_i32 s75, s34, 1
	s_nop 0
	v_addc_co_u32_e32 v1, vcc, 0, v1, vcc
	global_load_dword v26, v3, s[58:59]
	global_load_dword v27, v[0:1], off
	v_lshl_add_u64 v[0:1], s[42:43], 0, v[4:5]
	s_mov_b64 s[6:7], 0x23500000
	v_lshlrev_b32_e32 v6, 1, v2
	v_mov_b32_e32 v7, v5
	v_lshl_add_u64 v[0:1], v[0:1], 0, s[6:7]
	v_lshl_add_u64 v[2:3], s[60:61], 0, v[6:7]
	v_lshl_add_u64 v[4:5], s[64:65], 0, v[4:5]
	v_lshl_add_u64 v[6:7], s[62:63], 0, v[6:7]
	v_lshlrev_b32_e32 v8, 2, v19
	s_lshl_b32 s76, s75, 2
	s_mov_b64 s[68:69], 0
	s_movk_i32 s77, 0x3480
	v_mov_b32_e32 v28, 0x3a27c5ac
	s_mov_b32 s78, 0xf800000
	v_mov_b32_e32 v29, 0x260
	s_movk_i32 s79, 0x7ff
